# batched RSS->rstd pre-pass for the four RSS-using GEMMs (each wave takes whole tiles, 16 loads in flight) on top of v65
# baseline (speedup 1.0000x reference)
; #define LAS __attribute__((address_space(3)))
; __device__ __forceinline__ int opaque_tid() { int t = threadIdx.x; asm volatile("" : "+v"(t)); return t; }
; __device__ __forceinline__ float row_rstd(const float* RSS, int row) {
;   const f32x4* p = (const f32x4*)(RSS + (size_t)row * 16); f32x4 a = p[0], b = p[1], c = p[2], d = p[3];
;   float s = ((a[0] + a[1]) + (a[2] + a[3])) + ((b[0] + b[1]) + (b[2] + b[3])) + ((c[0] + c[1]) + (c[2] + c[3])) + ((d[0] + d[1]) + (d[2] + d[3]));
;   return rsqrtf(s * (1.f / 1024.f) + 1e-6f);
; }
; template <class Epi> __device__ __forceinline__ void run_gemm(LAS unsigned char* lds, const bf16_t* A, const bf16_t* Bt, int M, int N, int K, const Epi& E, const float* RSS = nullptr) {
;     ...
;   if (RSS) {
;     LAS float* rsl = (LAS float*)(lds + 131072); const int tid = opaque_tid(); Unit u;
;     for (int i = 0; S.next(i, u); ++i) if (tid < 256) rsl[i * 256 + tid] = row_rstd(RSS, u.pm * 256 + tid);
;     __syncthreads();
.LBB0_195:
	s_or_b64 exec, exec, s[22:23]
	s_waitcnt lgkmcnt(0)
	v_mov_b32_e32 v0, v214
	s_movk_i32 s6, 0x100
	s_barrier
	v_readlane_b32 s6, v255, 48
	s_lshr_b32 s34, s101, 6
	v_and_b32_e32 v1, 63, v0
	s_mul_i32 s35, s34, s90
	s_mul_hi_u32 s7, s34, s90
	s_add_u32 s22, s2, s35
	s_addc_u32 s23, s3, s7
	s_lshl_b32 s7, s34, 10
	s_add_i32 s7, s7, s6
	s_lshl_b64 s[34:35], s[90:91], 3
	v_lshl_add_u32 v20, v1, 2, s7
.Lrsl0_loop:
	v_cmp_gt_i64_e32 vcc, s[22:23], v[162:163]
	s_cbranch_vccnz .Lrsl0_done
	s_ashr_i32 s6, s22, 31
	s_lshr_b32 s6, s6, 29
	s_add_i32 s6, s22, s6
	s_ashr_i32 s7, s6, 3
	s_and_b32 s6, s6, -8
	s_sub_i32 s6, s22, s6
	s_cmp_lt_i32 s6, 0
	s_movk_i32 s12, 0x161
	s_cselect_b32 s12, s12, 0x160
	s_mul_i32 s6, s12, s6
	s_add_i32 s6, s6, s7
	s_mul_hi_i32 s7, s6, 0x2e8ba2e9
	s_lshr_b32 s12, s7, 31
	s_ashr_i32 s7, s7, 5
	s_add_i32 s7, s7, s12
	s_lshl_b32 s12, s7, 3
	s_sub_i32 s13, 0x80, s12
	s_min_i32 s13, s13, 8
	s_abs_i32 s13, s13
	v_cvt_f32_u32_e32 v2, s13
	s_sub_i32 s20, 0, s13
	s_mulk_i32 s7, 0xb0
	s_sub_i32 s6, s6, s7
	v_rcp_iflag_f32_e32 v2, v2
	s_ashr_i32 s7, s6, 31
	s_abs_i32 s6, s6
	v_mul_f32_e32 v2, 0x4f7ffffe, v2
	v_cvt_u32_f32_e32 v2, v2
	s_nop 0
	v_readfirstlane_b32 s38, v2
	s_mul_i32 s20, s20, s38
	s_mul_hi_u32 s20, s38, s20
	s_add_i32 s38, s38, s20
	s_mul_hi_u32 s20, s6, s38
	s_mul_i32 s20, s20, s13
	s_sub_i32 s6, s6, s20
	s_sub_i32 s20, s6, s13
	s_cmp_ge_u32 s6, s13
	s_cselect_b32 s6, s20, s6
	s_sub_i32 s20, s6, s13
	s_cmp_ge_u32 s6, s13
	s_cselect_b32 s6, s20, s6
	s_xor_b32 s6, s6, s7
	s_sub_i32 s6, s6, s7
	s_add_i32 s6, s6, s12
	v_lshl_add_u32 v2, s6, 8, v1
	v_lshlrev_b32_e32 v21, 6, v2
	global_load_dwordx4 v[48:51], v21, s[92:93]
	global_load_dwordx4 v[52:55], v21, s[92:93] offset:16
	global_load_dwordx4 v[56:59], v21, s[92:93] offset:32
	global_load_dwordx4 v[60:63], v21, s[92:93] offset:48
	v_add_u32_e32 v22, 0x1000, v21
	global_load_dwordx4 v[64:67], v22, s[92:93]
	global_load_dwordx4 v[68:71], v22, s[92:93] offset:16
	global_load_dwordx4 v[72:75], v22, s[92:93] offset:32
	global_load_dwordx4 v[76:79], v22, s[92:93] offset:48
	v_add_u32_e32 v23, 0x2000, v21
	global_load_dwordx4 v[80:83], v23, s[92:93]
	global_load_dwordx4 v[84:87], v23, s[92:93] offset:16
	global_load_dwordx4 v[88:91], v23, s[92:93] offset:32
	global_load_dwordx4 v[92:95], v23, s[92:93] offset:48
	v_add_u32_e32 v24, 0x3000, v21
	global_load_dwordx4 v[96:99], v24, s[92:93]
	global_load_dwordx4 v[100:103], v24, s[92:93] offset:16
	global_load_dwordx4 v[104:107], v24, s[92:93] offset:32
	global_load_dwordx4 v[108:111], v24, s[92:93] offset:48
	s_add_u32 s22, s22, s34
	s_addc_u32 s23, s23, s35
	s_waitcnt vmcnt(12)
	v_add_f32_e32 v48, v48, v49
	v_add_f32_e32 v50, v50, v51
	v_add_f32_e32 v48, v48, v50
	v_add_f32_e32 v52, v52, v53
	v_add_f32_e32 v54, v54, v55
	v_add_f32_e32 v52, v52, v54
	v_add_f32_e32 v56, v56, v57
	v_add_f32_e32 v58, v58, v59
	v_add_f32_e32 v56, v56, v58
	v_add_f32_e32 v60, v60, v61
	v_add_f32_e32 v62, v62, v63
	v_add_f32_e32 v60, v60, v62
	v_add_f32_e32 v48, v48, v52
	v_add_f32_e32 v48, v48, v56
	v_add_f32_e32 v48, v48, v60
	v_fmamk_f32 v48, v48, 0x3a800000, v217
	v_cmp_gt_f32_e32 vcc, 0x800000, v48
	v_mul_f32_e32 v49, 0x4b800000, v48
	s_nop 0
	v_cndmask_b32_e32 v48, v48, v49, vcc
	v_rsq_f32_e32 v48, v48
	s_nop 0
	v_mul_f32_e32 v49, 0x45800000, v48
	v_cndmask_b32_e32 v48, v48, v49, vcc
	ds_write_b32 v20, v48
	s_waitcnt vmcnt(8)
	v_add_f32_e32 v64, v64, v65
	v_add_f32_e32 v66, v66, v67
	v_add_f32_e32 v64, v64, v66
	v_add_f32_e32 v68, v68, v69
	v_add_f32_e32 v70, v70, v71
	v_add_f32_e32 v68, v68, v70
	v_add_f32_e32 v72, v72, v73
	v_add_f32_e32 v74, v74, v75
	v_add_f32_e32 v72, v72, v74
	v_add_f32_e32 v76, v76, v77
	v_add_f32_e32 v78, v78, v79
	v_add_f32_e32 v76, v76, v78
	v_add_f32_e32 v64, v64, v68
	v_add_f32_e32 v64, v64, v72
	v_add_f32_e32 v64, v64, v76
	v_fmamk_f32 v64, v64, 0x3a800000, v217
	v_cmp_gt_f32_e32 vcc, 0x800000, v64
	v_mul_f32_e32 v65, 0x4b800000, v64
	s_nop 0
	v_cndmask_b32_e32 v64, v64, v65, vcc
	v_rsq_f32_e32 v64, v64
	s_nop 0
	v_mul_f32_e32 v65, 0x45800000, v64
	v_cndmask_b32_e32 v64, v64, v65, vcc
	ds_write_b32 v20, v64 offset:256
	s_waitcnt vmcnt(4)
	v_add_f32_e32 v80, v80, v81
	v_add_f32_e32 v82, v82, v83
	v_add_f32_e32 v80, v80, v82
	v_add_f32_e32 v84, v84, v85
	v_add_f32_e32 v86, v86, v87
	v_add_f32_e32 v84, v84, v86
	v_add_f32_e32 v88, v88, v89
	v_add_f32_e32 v90, v90, v91
	v_add_f32_e32 v88, v88, v90
	v_add_f32_e32 v92, v92, v93
	v_add_f32_e32 v94, v94, v95
	v_add_f32_e32 v92, v92, v94
	v_add_f32_e32 v80, v80, v84
	v_add_f32_e32 v80, v80, v88
	v_add_f32_e32 v80, v80, v92
	v_fmamk_f32 v80, v80, 0x3a800000, v217
	v_cmp_gt_f32_e32 vcc, 0x800000, v80
	v_mul_f32_e32 v81, 0x4b800000, v80
	s_nop 0
	v_cndmask_b32_e32 v80, v80, v81, vcc
	v_rsq_f32_e32 v80, v80
	s_nop 0
	v_mul_f32_e32 v81, 0x45800000, v80
	v_cndmask_b32_e32 v80, v80, v81, vcc
	ds_write_b32 v20, v80 offset:512
	s_waitcnt vmcnt(0)
	v_add_f32_e32 v96, v96, v97
	v_add_f32_e32 v98, v98, v99
	v_add_f32_e32 v96, v96, v98
	v_add_f32_e32 v100, v100, v101
	v_add_f32_e32 v102, v102, v103
	v_add_f32_e32 v100, v100, v102
	v_add_f32_e32 v104, v104, v105
	v_add_f32_e32 v106, v106, v107
	v_add_f32_e32 v104, v104, v106
	v_add_f32_e32 v108, v108, v109
	v_add_f32_e32 v110, v110, v111
	v_add_f32_e32 v108, v108, v110
	v_add_f32_e32 v96, v96, v100
	v_add_f32_e32 v96, v96, v104
	v_add_f32_e32 v96, v96, v108
	v_fmamk_f32 v96, v96, 0x3a800000, v217
	v_cmp_gt_f32_e32 vcc, 0x800000, v96
	v_mul_f32_e32 v97, 0x4b800000, v96
	s_nop 0
	v_cndmask_b32_e32 v96, v96, v97, vcc
	v_rsq_f32_e32 v96, v96
	s_nop 0
	v_mul_f32_e32 v97, 0x45800000, v96
	v_cndmask_b32_e32 v96, v96, v97, vcc
	ds_write_b32 v20, v96 offset:768
	v_add_u32_e32 v20, 0x2000, v20
	s_branch .Lrsl0_loop
; __device__ __forceinline__ int opaque_tid() { int t = threadIdx.x; asm volatile("" : "+v"(t)); return t; }
; #define PG8_STAGE(bufoff, gbase, voff) do { _Pragma("unroll") for (int _i = 0; _i < 2; ++_i) \
;     __builtin_amdgcn_global_load_lds((const unsigned*)((const char*)(gbase) + (voff)[_i]), (LAS unsigned*)(lds + (bufoff) + ldsw + _i * 8192), 16, 0, 0); } while (0)
; #define PG8_BAR __builtin_amdgcn_s_barrier()
; template <class Epi, class Sched>
; __device__ __forceinline__ void gemm_phase(LAS unsigned char* lds, const Gemm g, const Sched& S, const Epi& E) {
;   const int tid = opaque_tid(), wid = __builtin_amdgcn_readfirstlane(tid >> 6), lane = tid & 63, wr = wid >> 2, wc = wid & 3, fr = lane & 15, fq = lane >> 4;
;   const int K = g.K, nt = K / BK;
;   unsigned voffA[2], voffB[2];
; #pragma unroll
;   for (int i = 0; i < 2; ++i) { int R, C; stage_rc(tid * 16 + i * 8192, R, C); const int Rb = Epi::PERM ? ((R & ~31) + perm32(R & 31)) : R;
;     voffA[i] = (unsigned)(R * K + C) * 2u; voffB[i] = (unsigned)(Rb * K + C) * 2u; }
;   const size_t kstep = (size_t)(BK * 2);
;   const size_t hstep = (size_t)HALF * K * 2;
;   const size_t tstep = 2 * hstep;
;   const unsigned ldsw = (unsigned)wid * 1024u;
;   const int aoff = lds_byte(wr * 64 + fr, fq * 8), boff = lds_byte(wc * 32 + fr, fq * 8);
;     ...
;   Unit cur, nxt; int ui = 0;
;   if (!S.next(0, cur)) return;
;   f32x4 acc[2][2][4][2];
; #pragma unroll
;   for (int a = 0; a < 2; ++a)
; #pragma unroll
;     for (int b = 0; b < 2; ++b)
; #pragma unroll
;       for (int m = 0; m < 4; ++m)
; #pragma unroll
;         for (int n = 0; n < 2; ++n) acc[a][b][m][n] = (f32x4){0.f, 0.f, 0.f, 0.f};
;   bf16x8 At[4][2], B0[2][2], B1[2][2];
;   const char* cA = (const char*)g.A + (size_t)cur.pm * tstep; const char* cB = (const char*)g.Bt + (size_t)cur.pn * tstep;
;   S.a_ready(cur);
;   PG8_STAGE(PG8_SB(0, 0), cB, voffB); PG8_STAGE(PG8_SA(0, 0), cA, voffA); PG8_STAGE(PG8_SB(0, 1), cB + hstep, voffB); PG8_STAGE(PG8_SA(0, 1), cA + hstep, voffA);
;   if (wr == 1) PG8_BAR;
.Lrsl0_done:
.LBB0_201:
	v_readlane_b32 s12, v251, 59
	v_mov_b32_e32 v2, v214
	v_readlane_b32 s13, v251, 60
	s_waitcnt lgkmcnt(0)
	s_barrier
	s_and_b64 vcc, exec, s[12:13]
	v_readfirstlane_b32 s6, v2
	s_cbranch_vccz .LBB0_213
	v_lshlrev_b32_e32 v4, 4, v2
	v_add_u32_e32 v1, 0x2000, v4
	v_ashrrev_i32_e32 v0, 31, v1
	v_lshrrev_b32_e32 v0, 22, v0
	v_add_u32_e32 v0, v1, v0
	v_ashrrev_i32_e32 v0, 10, v0
	v_mul_i32_i24_e32 v3, 0x400, v0
	v_sub_u32_e32 v1, v1, v3
	v_lshrrev_b32_e32 v3, 4, v1
	v_bitop3_b32 v3, v3, v1, 32 bitop3:0x6c
	v_ashrrev_i32_e32 v1, 31, v3
	v_lshrrev_b32_e32 v1, 26, v1
	v_add_u32_e32 v5, v3, v1
	v_lshlrev_b32_e32 v6, 3, v0
	v_ashrrev_i32_e32 v1, 6, v5
	v_and_b32_e32 v6, -16, v6
	v_add_u32_e32 v6, v1, v6
	v_and_b32_e32 v7, 3, v1
	s_mov_b32 s12, 0x1fffe0
	v_lshrrev_b32_e32 v8, 2, v6
	v_lshlrev_b32_e32 v9, 1, v6
	v_and_b32_e32 v5, 0xc0, v5
	v_and_or_b32 v7, v6, s12, v7
	v_and_b32_e32 v8, 4, v8
	v_and_b32_e32 v9, 24, v9
	v_sub_u32_e32 v3, v3, v5
	v_or3_b32 v7, v7, v8, v9
	v_lshlrev_b32_e32 v8, 5, v0
	v_ashrrev_i16_sdwa v3, v246, sext(v3) dst_sel:DWORD dst_unused:UNUSED_PAD src0_sel:DWORD src1_sel:BYTE_0
	v_and_b32_e32 v8, 32, v8
	v_bfe_i32 v3, v3, 0, 16
	v_add_lshl_u32 v5, v8, v3, 1
	v_lshl_add_u32 v128, v7, 11, v5
	v_lshl_add_u32 v130, v6, 11, v5
	v_bfe_i32 v5, v2, 27, 1
	v_lshrrev_b32_e32 v5, 22, v5
	v_add_u32_e32 v5, v4, v5
	v_and_b32_e32 v5, 0xfffffc00, v5
	v_sub_u32_e32 v4, v4, v5
	v_lshrrev_b32_e32 v5, 4, v4
	v_bitop3_b32 v6, v5, v4, 32 bitop3:0x6c
	v_ashrrev_i32_e32 v5, 31, v2
	v_lshrrev_b32_e32 v5, 26, v5
	v_ashrrev_i32_e32 v4, 31, v4
	v_add_u32_e32 v5, v2, v5
	v_lshrrev_b32_e32 v4, 26, v4
	v_ashrrev_i32_e32 v5, 6, v5
	v_add_u32_e32 v4, v6, v4
	v_lshlrev_b32_e32 v7, 3, v5
	v_ashrrev_i32_e32 v4, 6, v4
	v_and_b32_e32 v7, -16, v7
	v_add_u32_e32 v7, v4, v7
	v_and_b32_e32 v8, 3, v4
	v_lshrrev_b32_e32 v9, 2, v7
	v_lshlrev_b32_e32 v10, 1, v7
	v_and_or_b32 v8, v7, s12, v8
	v_and_b32_e32 v9, 4, v9
	v_and_b32_e32 v10, 24, v10
	v_or3_b32 v8, v8, v9, v10
	v_mul_i32_i24_e32 v10, 64, v4
	v_sub_u32_e32 v6, v6, v10
	s_ashr_i32 s20, s6, 6
	v_lshlrev_b32_e32 v9, 5, v5
	v_ashrrev_i16_sdwa v6, v246, sext(v6) dst_sel:DWORD dst_unused:UNUSED_PAD src0_sel:DWORD src1_sel:BYTE_0
	s_lshl_b32 s7, s20, 10
	v_and_b32_e32 v9, 32, v9
	v_bfe_i32 v6, v6, 0, 16
	v_add_lshl_u32 v9, v9, v6, 1
	s_add_i32 s12, s7, 0
	v_readlane_b32 s22, v252, 8
	v_lshl_add_u32 v132, v8, 11, v9
	s_add_i32 m0, s12, 0x10000
	v_readlane_b32 s23, v252, 9
	v_lshl_add_u32 v134, v7, 11, v9
	s_add_i32 s13, s12, 0x2000
	s_add_i32 s48, s12, 0x4000
	s_add_i32 s49, s12, 0x6000
	v_mov_b32_e32 v225, 1
	global_load_lds_dwordx4 v132, s[22:23]
	s_add_i32 m0, s12, 0x12000
	s_nop 0
	global_load_lds_dwordx4 v128, s[22:23]
	v_readlane_b32 s22, v252, 4
	s_mov_b32 m0, s12
	v_readlane_b32 s23, v252, 5
	s_nop 4
	global_load_lds_dwordx4 v134, s[22:23]
	s_mov_b32 m0, s13
	s_nop 0
	global_load_lds_dwordx4 v130, s[22:23]
	v_readlane_b32 s22, v252, 2
	s_add_i32 m0, s12, 0x14000
	v_readlane_b32 s23, v252, 3
	s_nop 4
	global_load_lds_dwordx4 v132, s[22:23]
	s_add_i32 m0, s12, 0x16000
	s_nop 0
	global_load_lds_dwordx4 v128, s[22:23]
	v_readlane_b32 s22, v252, 6
	s_mov_b32 m0, s48
	v_readlane_b32 s23, v252, 7
	s_nop 4
	global_load_lds_dwordx4 v134, s[22:23]
	s_mov_b32 m0, s49
	s_nop 0
	global_load_lds_dwordx4 v130, s[22:23]
	s_ashr_i32 s22, s6, 8
	s_cmp_lg_u32 s22, 1
	s_cbranch_scc1 .LBB0_204
	s_barrier

; #define LAS __attribute__((address_space(3)))
; __device__ __forceinline__ int opaque_tid() { int t = threadIdx.x; asm volatile("" : "+v"(t)); return t; }
; __device__ __forceinline__ float row_rstd(const float* RSS, int row) {
;   const f32x4* p = (const f32x4*)(RSS + (size_t)row * 16); f32x4 a = p[0], b = p[1], c = p[2], d = p[3];
;   float s = ((a[0] + a[1]) + (a[2] + a[3])) + ((b[0] + b[1]) + (b[2] + b[3])) + ((c[0] + c[1]) + (c[2] + c[3])) + ((d[0] + d[1]) + (d[2] + d[3]));
;   return rsqrtf(s * (1.f / 1024.f) + 1e-6f);
; }
; template <class Epi> __device__ __forceinline__ void run_gemm(LAS unsigned char* lds, const bf16_t* A, const bf16_t* Bt, int M, int N, int K, const Epi& E, const float* RSS = nullptr) {
;     ...
;   if (RSS) {
;     LAS float* rsl = (LAS float*)(lds + 131072); const int tid = opaque_tid(); Unit u;
;     for (int i = 0; S.next(i, u); ++i) if (tid < 256) rsl[i * 256 + tid] = row_rstd(RSS, u.pm * 256 + tid);
;     __syncthreads();
.Lrsl1_loop:
	v_cmp_gt_i64_e32 vcc, s[22:23], v[170:171]
	s_cbranch_vccnz .Lrsl1_done
	s_ashr_i32 s6, s22, 31
	s_lshr_b32 s6, s6, 29
	s_add_i32 s6, s22, s6
	s_ashr_i32 s7, s6, 3
	s_and_b32 s6, s6, -8
	s_sub_i32 s6, s22, s6
	s_cmp_lt_i32 s6, 0
	s_movk_i32 s12, 0xc1
	s_cselect_b32 s12, s12, 0xc0
	s_mul_i32 s6, s12, s6
	s_add_i32 s6, s6, s7
	s_mul_hi_i32 s7, s6, 0x2aaaaaab
	s_lshr_b32 s12, s7, 31
	s_ashr_i32 s7, s7, 4
	s_add_i32 s7, s7, s12
	s_lshl_b32 s12, s7, 3
	s_mulk_i32 s7, 0x60
	s_sub_i32 s6, s6, s7
	s_sub_i32 s7, 0x80, s12
	s_min_i32 s7, s7, 8
	s_abs_i32 s7, s7
	v_cvt_f32_u32_e32 v2, s7
	s_sub_i32 s20, 0, s7
	s_ashr_i32 s13, s6, 31
	s_abs_i32 s6, s6
	v_rcp_iflag_f32_e32 v2, v2
	s_nop 0
	v_mul_f32_e32 v2, 0x4f7ffffe, v2
	v_cvt_u32_f32_e32 v2, v2
	s_nop 0
	v_readfirstlane_b32 s36, v2
	s_mul_i32 s20, s20, s36
	s_mul_hi_u32 s20, s36, s20
	s_add_i32 s36, s36, s20
	s_mul_hi_u32 s20, s6, s36
	s_mul_i32 s20, s20, s7
	s_sub_i32 s6, s6, s20
	s_sub_i32 s20, s6, s7
	s_cmp_ge_u32 s6, s7
	s_cselect_b32 s6, s20, s6
	s_sub_i32 s20, s6, s7
	s_cmp_ge_u32 s6, s7
	s_cselect_b32 s6, s20, s6
	s_xor_b32 s6, s6, s13
	s_sub_i32 s6, s6, s13
	s_add_i32 s6, s6, s12
	v_lshl_add_u32 v2, s6, 8, v1
	v_lshlrev_b32_e32 v21, 6, v2
	global_load_dwordx4 v[48:51], v21, s[92:93]
	global_load_dwordx4 v[52:55], v21, s[92:93] offset:16
	global_load_dwordx4 v[56:59], v21, s[92:93] offset:32
	global_load_dwordx4 v[60:63], v21, s[92:93] offset:48
	v_add_u32_e32 v22, 0x1000, v21
	global_load_dwordx4 v[64:67], v22, s[92:93]
	global_load_dwordx4 v[68:71], v22, s[92:93] offset:16
	global_load_dwordx4 v[72:75], v22, s[92:93] offset:32
	global_load_dwordx4 v[76:79], v22, s[92:93] offset:48
	v_add_u32_e32 v23, 0x2000, v21
	global_load_dwordx4 v[80:83], v23, s[92:93]
	global_load_dwordx4 v[84:87], v23, s[92:93] offset:16
	global_load_dwordx4 v[88:91], v23, s[92:93] offset:32
	global_load_dwordx4 v[92:95], v23, s[92:93] offset:48
	v_add_u32_e32 v24, 0x3000, v21
	global_load_dwordx4 v[96:99], v24, s[92:93]
	global_load_dwordx4 v[100:103], v24, s[92:93] offset:16
	global_load_dwordx4 v[104:107], v24, s[92:93] offset:32
	global_load_dwordx4 v[108:111], v24, s[92:93] offset:48
	s_add_u32 s22, s22, s34
	s_addc_u32 s23, s23, s35
	s_waitcnt vmcnt(12)
	v_add_f32_e32 v48, v48, v49
	v_add_f32_e32 v50, v50, v51
	v_add_f32_e32 v48, v48, v50
	v_add_f32_e32 v52, v52, v53
	v_add_f32_e32 v54, v54, v55
	v_add_f32_e32 v52, v52, v54
	v_add_f32_e32 v56, v56, v57
	v_add_f32_e32 v58, v58, v59
	v_add_f32_e32 v56, v56, v58
	v_add_f32_e32 v60, v60, v61
	v_add_f32_e32 v62, v62, v63
	v_add_f32_e32 v60, v60, v62
	v_add_f32_e32 v48, v48, v52
	v_add_f32_e32 v48, v48, v56
	v_add_f32_e32 v48, v48, v60
	v_fmamk_f32 v48, v48, 0x3a800000, v217
	v_cmp_gt_f32_e32 vcc, 0x800000, v48
	v_mul_f32_e32 v49, 0x4b800000, v48
	s_nop 0
	v_cndmask_b32_e32 v48, v48, v49, vcc
	v_rsq_f32_e32 v48, v48
	s_nop 0
	v_mul_f32_e32 v49, 0x45800000, v48
	v_cndmask_b32_e32 v48, v48, v49, vcc
	ds_write_b32 v20, v48
	s_waitcnt vmcnt(8)
	v_add_f32_e32 v64, v64, v65
	v_add_f32_e32 v66, v66, v67
	v_add_f32_e32 v64, v64, v66
	v_add_f32_e32 v68, v68, v69
	v_add_f32_e32 v70, v70, v71
	v_add_f32_e32 v68, v68, v70
	v_add_f32_e32 v72, v72, v73
	v_add_f32_e32 v74, v74, v75
	v_add_f32_e32 v72, v72, v74
	v_add_f32_e32 v76, v76, v77
	v_add_f32_e32 v78, v78, v79
	v_add_f32_e32 v76, v76, v78
	v_add_f32_e32 v64, v64, v68
	v_add_f32_e32 v64, v64, v72
	v_add_f32_e32 v64, v64, v76
	v_fmamk_f32 v64, v64, 0x3a800000, v217
	v_cmp_gt_f32_e32 vcc, 0x800000, v64
	v_mul_f32_e32 v65, 0x4b800000, v64
	s_nop 0
	v_cndmask_b32_e32 v64, v64, v65, vcc
	v_rsq_f32_e32 v64, v64
	s_nop 0
	v_mul_f32_e32 v65, 0x45800000, v64
	v_cndmask_b32_e32 v64, v64, v65, vcc
	ds_write_b32 v20, v64 offset:256
	s_waitcnt vmcnt(4)
	v_add_f32_e32 v80, v80, v81
	v_add_f32_e32 v82, v82, v83
	v_add_f32_e32 v80, v80, v82
	v_add_f32_e32 v84, v84, v85
	v_add_f32_e32 v86, v86, v87
	v_add_f32_e32 v84, v84, v86
	v_add_f32_e32 v88, v88, v89
	v_add_f32_e32 v90, v90, v91
	v_add_f32_e32 v88, v88, v90
	v_add_f32_e32 v92, v92, v93
	v_add_f32_e32 v94, v94, v95
	v_add_f32_e32 v92, v92, v94
	v_add_f32_e32 v80, v80, v84
	v_add_f32_e32 v80, v80, v88
	v_add_f32_e32 v80, v80, v92
	v_fmamk_f32 v80, v80, 0x3a800000, v217
	v_cmp_gt_f32_e32 vcc, 0x800000, v80
	v_mul_f32_e32 v81, 0x4b800000, v80
	s_nop 0
	v_cndmask_b32_e32 v80, v80, v81, vcc
	v_rsq_f32_e32 v80, v80
	s_nop 0
	v_mul_f32_e32 v81, 0x45800000, v80
	v_cndmask_b32_e32 v80, v80, v81, vcc
	ds_write_b32 v20, v80 offset:512
	s_waitcnt vmcnt(0)
	v_add_f32_e32 v96, v96, v97
	v_add_f32_e32 v98, v98, v99
	v_add_f32_e32 v96, v96, v98
	v_add_f32_e32 v100, v100, v101
	v_add_f32_e32 v102, v102, v103
	v_add_f32_e32 v100, v100, v102
	v_add_f32_e32 v104, v104, v105
	v_add_f32_e32 v106, v106, v107
	v_add_f32_e32 v104, v104, v106
	v_add_f32_e32 v108, v108, v109
	v_add_f32_e32 v110, v110, v111
	v_add_f32_e32 v108, v108, v110
	v_add_f32_e32 v96, v96, v100
	v_add_f32_e32 v96, v96, v104
	v_add_f32_e32 v96, v96, v108
	v_fmamk_f32 v96, v96, 0x3a800000, v217
	v_cmp_gt_f32_e32 vcc, 0x800000, v96
	v_mul_f32_e32 v97, 0x4b800000, v96
	s_nop 0
	v_cndmask_b32_e32 v96, v96, v97, vcc
	v_rsq_f32_e32 v96, v96
	s_nop 0
	v_mul_f32_e32 v97, 0x45800000, v96
	v_cndmask_b32_e32 v96, v96, v97, vcc
	ds_write_b32 v20, v96 offset:768
	v_add_u32_e32 v20, 0x2000, v20
	s_branch .Lrsl1_loop
; #define PG8_STAGE(bufoff, gbase, voff) do { _Pragma("unroll") for (int _i = 0; _i < 2; ++_i) \
;     __builtin_amdgcn_global_load_lds((const unsigned*)((const char*)(gbase) + (voff)[_i]), (LAS unsigned*)(lds + (bufoff) + ldsw + _i * 8192), 16, 0, 0); } while (0)
; #define PG8_BAR __builtin_amdgcn_s_barrier()
; template <class Epi, class Sched>
; __device__ __forceinline__ void gemm_phase(LAS unsigned char* lds, const Gemm g, const Sched& S, const Epi& E) {
;     ...
;   for (int i = 0; i < 2; ++i) { int R, C; stage_rc(tid * 16 + i * 8192, R, C); const int Rb = Epi::PERM ? ((R & ~31) + perm32(R & 31)) : R;
;     voffA[i] = (unsigned)(R * K + C) * 2u; voffB[i] = (unsigned)(Rb * K + C) * 2u; }
;   const size_t kstep = (size_t)(BK * 2);
;   const size_t hstep = (size_t)HALF * K * 2;
;   const size_t tstep = 2 * hstep;
;   const unsigned ldsw = (unsigned)wid * 1024u;
;   const int aoff = lds_byte(wr * 64 + fr, fq * 8), boff = lds_byte(wc * 32 + fr, fq * 8);
;     ...
;   Unit cur, nxt; int ui = 0;
;   if (!S.next(0, cur)) return;
;   f32x4 acc[2][2][4][2];
; #pragma unroll
;   for (int a = 0; a < 2; ++a)
; #pragma unroll
;     for (int b = 0; b < 2; ++b)
; #pragma unroll
;       for (int m = 0; m < 4; ++m)
; #pragma unroll
;         for (int n = 0; n < 2; ++n) acc[a][b][m][n] = (f32x4){0.f, 0.f, 0.f, 0.f};
;   bf16x8 At[4][2], B0[2][2], B1[2][2];
;   const char* cA = (const char*)g.A + (size_t)cur.pm * tstep; const char* cB = (const char*)g.Bt + (size_t)cur.pn * tstep;
;   S.a_ready(cur);
;   PG8_STAGE(PG8_SB(0, 0), cB, voffB); PG8_STAGE(PG8_SA(0, 0), cA, voffA); PG8_STAGE(PG8_SB(0, 1), cB + hstep, voffB); PG8_STAGE(PG8_SA(0, 1), cA + hstep, voffA);
;   if (wr == 1) PG8_BAR;
; template <class Epi> __device__ __forceinline__ void run_gemm(LAS unsigned char* lds, const bf16_t* A, const bf16_t* Bt, int M, int N, int K, const Epi& E, const float* RSS = nullptr) {
;     ...
;     for (int i = 0; S.next(i, u); ++i) if (tid < 256) rsl[i * 256 + tid] = row_rstd(RSS, u.pm * 256 + tid);
;     __syncthreads();
.Lrsl1_done:
.LBB0_359:
	v_readlane_b32 s6, v252, 14
	v_mov_b32_e32 v6, v214
	v_readlane_b32 s7, v252, 15
	s_waitcnt lgkmcnt(0)
	s_barrier
	s_and_b64 vcc, exec, s[6:7]
	v_readfirstlane_b32 s66, v6
	s_cbranch_vccz .LBB0_375
	v_lshlrev_b32_e32 v3, 4, v6
	v_add_u32_e32 v1, 0x2000, v3
	v_ashrrev_i32_e32 v0, 31, v1
	v_lshrrev_b32_e32 v0, 22, v0
	v_add_u32_e32 v0, v1, v0
	v_ashrrev_i32_e32 v0, 10, v0
	v_mul_i32_i24_e32 v2, 0x400, v0
	v_sub_u32_e32 v1, v1, v2
	v_lshrrev_b32_e32 v2, 4, v1
	v_bitop3_b32 v2, v2, v1, 32 bitop3:0x6c
	v_ashrrev_i32_e32 v1, 31, v2
	v_lshrrev_b32_e32 v1, 26, v1
	v_add_u32_e32 v4, v2, v1
	v_lshlrev_b32_e32 v5, 3, v0
	v_ashrrev_i32_e32 v1, 6, v4
	v_and_b32_e32 v5, -16, v5
	v_add_u32_e32 v5, v1, v5
	v_and_b32_e32 v7, 3, v1
	s_mov_b32 s12, 0x1fffe0
	v_lshrrev_b32_e32 v8, 2, v5
	v_lshlrev_b32_e32 v9, 1, v5
	v_and_b32_e32 v4, 0xc0, v4
	v_and_or_b32 v7, v5, s12, v7
	v_and_b32_e32 v8, 4, v8
	v_and_b32_e32 v9, 24, v9
	v_sub_u32_e32 v2, v2, v4
	v_or3_b32 v7, v7, v8, v9
	v_lshlrev_b32_e32 v8, 5, v0
	v_ashrrev_i16_sdwa v2, v246, sext(v2) dst_sel:DWORD dst_unused:UNUSED_PAD src0_sel:DWORD src1_sel:BYTE_0
	v_and_b32_e32 v8, 32, v8
	v_bfe_i32 v2, v2, 0, 16
	v_add_lshl_u32 v4, v8, v2, 1
	v_lshl_add_u32 v144, v7, 11, v4
	v_lshl_add_u32 v146, v5, 11, v4
	v_bfe_i32 v4, v6, 27, 1
	v_lshrrev_b32_e32 v4, 22, v4
	v_add_u32_e32 v4, v3, v4
	v_and_b32_e32 v4, 0xfffffc00, v4
	v_sub_u32_e32 v3, v3, v4
	v_lshrrev_b32_e32 v4, 4, v3
	v_bitop3_b32 v5, v4, v3, 32 bitop3:0x6c
	v_ashrrev_i32_e32 v4, 31, v6
	v_lshrrev_b32_e32 v4, 26, v4
	v_ashrrev_i32_e32 v3, 31, v3
	v_add_u32_e32 v4, v6, v4
	v_lshrrev_b32_e32 v3, 26, v3
	v_ashrrev_i32_e32 v4, 6, v4
	v_add_u32_e32 v3, v5, v3
	v_lshlrev_b32_e32 v7, 3, v4
	v_ashrrev_i32_e32 v3, 6, v3
	v_and_b32_e32 v7, -16, v7
	v_add_u32_e32 v7, v3, v7
	v_and_b32_e32 v8, 3, v3
	v_lshrrev_b32_e32 v9, 2, v7
	v_lshlrev_b32_e32 v10, 1, v7
	v_and_or_b32 v8, v7, s12, v8
	v_and_b32_e32 v9, 4, v9
	v_and_b32_e32 v10, 24, v10
	v_or3_b32 v8, v8, v9, v10
	v_mul_i32_i24_e32 v10, 64, v3
	v_sub_u32_e32 v5, v5, v10
	s_ashr_i32 s6, s66, 6
	v_lshlrev_b32_e32 v9, 5, v4
	v_ashrrev_i16_sdwa v5, v246, sext(v5) dst_sel:DWORD dst_unused:UNUSED_PAD src0_sel:DWORD src1_sel:BYTE_0
	s_lshl_b32 s7, s6, 10
	v_and_b32_e32 v9, 32, v9
	v_bfe_i32 v5, v5, 0, 16
	v_add_lshl_u32 v9, v9, v5, 1
	s_add_i32 s12, s7, 0
	v_readlane_b32 s22, v252, 27
	v_lshl_add_u32 v148, v8, 11, v9
	s_add_i32 m0, s12, 0x10000
	v_readlane_b32 s23, v252, 28
	v_lshl_add_u32 v150, v7, 11, v9
	s_add_i32 s13, s12, 0x2000
	s_add_i32 s20, s12, 0x4000
	s_add_i32 s48, s12, 0x6000
	s_nop 0
	global_load_lds_dwordx4 v148, s[22:23]
	s_add_i32 m0, s12, 0x12000
	s_nop 0
	global_load_lds_dwordx4 v144, s[22:23]
	v_readlane_b32 s22, v252, 23
	s_mov_b32 m0, s12
	v_readlane_b32 s23, v252, 24
	s_nop 4
	global_load_lds_dwordx4 v150, s[22:23]
	s_mov_b32 m0, s13
	s_nop 0
	global_load_lds_dwordx4 v146, s[22:23]
	v_readlane_b32 s22, v252, 21
	s_add_i32 m0, s12, 0x14000
	v_readlane_b32 s23, v252, 22
	s_nop 4
	global_load_lds_dwordx4 v148, s[22:23]
	s_add_i32 m0, s12, 0x16000
	s_nop 0
	global_load_lds_dwordx4 v144, s[22:23]
	v_readlane_b32 s22, v252, 25
	s_mov_b32 m0, s20
	v_readlane_b32 s23, v252, 26
	s_nop 4
	global_load_lds_dwordx4 v150, s[22:23]
	s_mov_b32 m0, s48
	s_nop 0
	global_load_lds_dwordx4 v146, s[22:23]
	s_ashr_i32 s22, s66, 8
	s_cmp_lg_u32 s22, 1
	s_cbranch_scc1 .LBB0_362
	s_barrier

; #define PG8_STAGE(bufoff, gbase, voff) do { _Pragma("unroll") for (int _i = 0; _i < 2; ++_i) \
;     __builtin_amdgcn_global_load_lds((const unsigned*)((const char*)(gbase) + (voff)[_i]), (LAS unsigned*)(lds + (bufoff) + ldsw + _i * 8192), 16, 0, 0); } while (0)
; #define PG8_BAR __builtin_amdgcn_s_barrier()
; template <class Epi, class Sched>
; __device__ __forceinline__ void gemm_phase(LAS unsigned char* lds, const Gemm g, const Sched& S, const Epi& E) {
;     ...
;   for (int i = 0; i < 2; ++i) { int R, C; stage_rc(tid * 16 + i * 8192, R, C); const int Rb = Epi::PERM ? ((R & ~31) + perm32(R & 31)) : R;
;     voffA[i] = (unsigned)(R * K + C) * 2u; voffB[i] = (unsigned)(Rb * K + C) * 2u; }
;   const size_t kstep = (size_t)(BK * 2);
;   const size_t hstep = (size_t)HALF * K * 2;
;   const size_t tstep = 2 * hstep;
;   const unsigned ldsw = (unsigned)wid * 1024u;
;   const int aoff = lds_byte(wr * 64 + fr, fq * 8), boff = lds_byte(wc * 32 + fr, fq * 8);
;     ...
;   Unit cur, nxt; int ui = 0;
;   if (!S.next(0, cur)) return;
;   f32x4 acc[2][2][4][2];
; #pragma unroll
;   for (int a = 0; a < 2; ++a)
; #pragma unroll
;     for (int b = 0; b < 2; ++b)
; #pragma unroll
;       for (int m = 0; m < 4; ++m)
; #pragma unroll
;         for (int n = 0; n < 2; ++n) acc[a][b][m][n] = (f32x4){0.f, 0.f, 0.f, 0.f};
;   bf16x8 At[4][2], B0[2][2], B1[2][2];
;   const char* cA = (const char*)g.A + (size_t)cur.pm * tstep; const char* cB = (const char*)g.Bt + (size_t)cur.pn * tstep;
;   S.a_ready(cur);
;   PG8_STAGE(PG8_SB(0, 0), cB, voffB); PG8_STAGE(PG8_SA(0, 0), cA, voffA); PG8_STAGE(PG8_SB(0, 1), cB + hstep, voffB); PG8_STAGE(PG8_SA(0, 1), cA + hstep, voffA);
;   if (wr == 1) PG8_BAR;
; template <class Epi> __device__ __forceinline__ void run_gemm(LAS unsigned char* lds, const bf16_t* A, const bf16_t* Bt, int M, int N, int K, const Epi& E, const float* RSS = nullptr) {
;     ...
;     for (int i = 0; S.next(i, u); ++i) if (tid < 256) rsl[i * 256 + tid] = row_rstd(RSS, u.pm * 256 + tid);
;     __syncthreads();
.Lrsl2_done:
.LBB0_699:
	v_readlane_b32 s6, v252, 14
	v_mov_b32_e32 v2, v214
	v_readlane_b32 s7, v252, 15
	s_waitcnt lgkmcnt(0)
	s_barrier
	s_and_b64 vcc, exec, s[6:7]
	v_readfirstlane_b32 s20, v2
	s_cbranch_vccz .LBB0_715
	v_lshlrev_b32_e32 v4, 4, v2
	v_add_u32_e32 v1, 0x2000, v4
	v_ashrrev_i32_e32 v0, 31, v1
	v_lshrrev_b32_e32 v0, 22, v0
	v_add_u32_e32 v0, v1, v0
	v_ashrrev_i32_e32 v0, 10, v0
	v_mul_i32_i24_e32 v3, 0x400, v0
	v_sub_u32_e32 v1, v1, v3
	v_lshrrev_b32_e32 v3, 4, v1
	v_bitop3_b32 v3, v3, v1, 32 bitop3:0x6c
	v_ashrrev_i32_e32 v1, 31, v3
	v_lshrrev_b32_e32 v1, 26, v1
	v_add_u32_e32 v5, v3, v1
	v_lshlrev_b32_e32 v6, 3, v0
	v_ashrrev_i32_e32 v1, 6, v5
	v_and_b32_e32 v6, -16, v6
	v_add_u32_e32 v6, v1, v6
	v_and_b32_e32 v7, 3, v1
	s_mov_b32 s7, 0x1fffe0
	v_lshrrev_b32_e32 v8, 2, v6
	v_lshlrev_b32_e32 v9, 1, v6
	v_and_b32_e32 v5, 0xc0, v5
	v_and_or_b32 v7, v6, s7, v7
	v_and_b32_e32 v8, 4, v8
	v_and_b32_e32 v9, 24, v9
	v_sub_u32_e32 v3, v3, v5
	v_or3_b32 v7, v7, v8, v9
	v_lshlrev_b32_e32 v8, 5, v0
	v_ashrrev_i16_sdwa v3, v246, sext(v3) dst_sel:DWORD dst_unused:UNUSED_PAD src0_sel:DWORD src1_sel:BYTE_0
	v_and_b32_e32 v8, 32, v8
	v_bfe_i32 v3, v3, 0, 16
	v_add_lshl_u32 v5, v8, v3, 1
	v_lshl_add_u32 v156, v7, 11, v5
	v_lshl_add_u32 v158, v6, 11, v5
	v_bfe_i32 v5, v2, 27, 1
	v_lshrrev_b32_e32 v5, 22, v5
	v_add_u32_e32 v5, v4, v5
	v_and_b32_e32 v5, 0xfffffc00, v5
	v_sub_u32_e32 v4, v4, v5
	v_lshrrev_b32_e32 v5, 4, v4
	v_bitop3_b32 v6, v5, v4, 32 bitop3:0x6c
	v_ashrrev_i32_e32 v5, 31, v2
	v_lshrrev_b32_e32 v5, 26, v5
	v_ashrrev_i32_e32 v4, 31, v4
	v_add_u32_e32 v5, v2, v5
	v_lshrrev_b32_e32 v4, 26, v4
	v_ashrrev_i32_e32 v5, 6, v5
	v_add_u32_e32 v4, v6, v4
	v_lshlrev_b32_e32 v7, 3, v5
	v_ashrrev_i32_e32 v4, 6, v4
	v_and_b32_e32 v7, -16, v7
	v_add_u32_e32 v7, v4, v7
	v_and_b32_e32 v8, 3, v4
	v_lshrrev_b32_e32 v9, 2, v7
	v_lshlrev_b32_e32 v10, 1, v7
	v_and_or_b32 v8, v7, s7, v8
	v_and_b32_e32 v9, 4, v9
	v_and_b32_e32 v10, 24, v10
	v_or3_b32 v8, v8, v9, v10
	v_mul_i32_i24_e32 v10, 64, v4
	v_sub_u32_e32 v6, v6, v10
	s_ashr_i32 s6, s20, 6
	v_lshlrev_b32_e32 v9, 5, v5
	v_ashrrev_i16_sdwa v6, v246, sext(v6) dst_sel:DWORD dst_unused:UNUSED_PAD src0_sel:DWORD src1_sel:BYTE_0
	s_lshl_b32 s64, s6, 10
	v_and_b32_e32 v9, 32, v9
	v_bfe_i32 v6, v6, 0, 16
	v_add_lshl_u32 v9, v9, v6, 1
	s_add_i32 s65, s64, 0
	v_readlane_b32 s12, v252, 51
	v_lshl_add_u32 v174, v8, 11, v9
	s_add_i32 m0, s65, 0x10000
	v_readlane_b32 s13, v252, 52
	v_lshl_add_u32 v176, v7, 11, v9
	s_add_i32 s51, s65, 0x2000
	s_add_i32 s62, s65, 0x4000
	s_add_i32 s63, s65, 0x6000
	s_ashr_i32 s7, s20, 8
	global_load_lds_dwordx4 v174, s[12:13]
	s_add_i32 m0, s65, 0x12000
	v_writelane_b32 v255, s20, 60
	global_load_lds_dwordx4 v156, s[12:13]
	v_readlane_b32 s12, v252, 23
	s_mov_b32 m0, s65
	v_readlane_b32 s13, v252, 24
	s_nop 4
	global_load_lds_dwordx4 v176, s[12:13]
	s_mov_b32 m0, s51
	s_nop 0
	global_load_lds_dwordx4 v158, s[12:13]
	v_readlane_b32 s12, v252, 49
	s_add_i32 m0, s65, 0x14000
	v_readlane_b32 s13, v252, 50
	s_nop 4
	global_load_lds_dwordx4 v174, s[12:13]
	s_add_i32 m0, s65, 0x16000
	s_cmp_lg_u32 s7, 1
	global_load_lds_dwordx4 v156, s[12:13]
	v_readlane_b32 s12, v252, 25
	s_mov_b32 m0, s62
	v_readlane_b32 s13, v252, 26
	s_nop 4
	global_load_lds_dwordx4 v176, s[12:13]
	s_mov_b32 m0, s63
	s_nop 0
	global_load_lds_dwordx4 v158, s[12:13]
	s_cbranch_scc1 .LBB0_702
	s_barrier

; #define LAS __attribute__((address_space(3)))
; __device__ __forceinline__ int opaque_tid() { int t = threadIdx.x; asm volatile("" : "+v"(t)); return t; }
; __device__ __forceinline__ float row_rstd(const float* RSS, int row) {
;   const f32x4* p = (const f32x4*)(RSS + (size_t)row * 16); f32x4 a = p[0], b = p[1], c = p[2], d = p[3];
;   float s = ((a[0] + a[1]) + (a[2] + a[3])) + ((b[0] + b[1]) + (b[2] + b[3])) + ((c[0] + c[1]) + (c[2] + c[3])) + ((d[0] + d[1]) + (d[2] + d[3]));
;   return rsqrtf(s * (1.f / 1024.f) + 1e-6f);
; }
; template <class Epi> __device__ __forceinline__ void run_gemm(LAS unsigned char* lds, const bf16_t* A, const bf16_t* Bt, int M, int N, int K, const Epi& E, const float* RSS = nullptr) {
;     ...
;   if (RSS) {
;     LAS float* rsl = (LAS float*)(lds + 131072); const int tid = opaque_tid(); Unit u;
;     for (int i = 0; S.next(i, u); ++i) if (tid < 256) rsl[i * 256 + tid] = row_rstd(RSS, u.pm * 256 + tid);
.Lrsl4_loop:
	v_cmp_gt_i64_e32 vcc, s[22:23], v[162:163]
	s_cbranch_vccnz .Lrsl4_done
	s_ashr_i32 s6, s22, 31
	s_lshr_b32 s6, s6, 29
	s_add_i32 s6, s22, s6
	s_ashr_i32 s7, s6, 3
	s_and_b32 s6, s6, -8
	s_sub_i32 s6, s22, s6
	s_cmp_lt_i32 s6, 0
	s_movk_i32 s12, 0x161
	s_cselect_b32 s12, s12, 0x160
	s_mul_i32 s6, s12, s6
	s_add_i32 s6, s6, s7
	s_mul_hi_i32 s7, s6, 0x2e8ba2e9
	s_lshr_b32 s12, s7, 31
	s_ashr_i32 s7, s7, 5
	s_add_i32 s7, s7, s12
	s_lshl_b32 s12, s7, 3
	s_mulk_i32 s7, 0xb0
	s_sub_i32 s6, s6, s7
	s_sub_i32 s7, 0x80, s12
	s_min_i32 s7, s7, 8
	s_abs_i32 s7, s7
	v_cvt_f32_u32_e32 v2, s7
	s_sub_i32 s20, 0, s7
	s_ashr_i32 s13, s6, 31
	s_abs_i32 s6, s6
	v_rcp_iflag_f32_e32 v2, v2
	s_nop 0
	v_mul_f32_e32 v2, 0x4f7ffffe, v2
	v_cvt_u32_f32_e32 v2, v2
	s_nop 0
	v_readfirstlane_b32 s36, v2
	s_mul_i32 s20, s20, s36
	s_mul_hi_u32 s20, s36, s20
	s_add_i32 s36, s36, s20
	s_mul_hi_u32 s20, s6, s36
	s_mul_i32 s20, s20, s7
	s_sub_i32 s6, s6, s20
	s_sub_i32 s20, s6, s7
	s_cmp_ge_u32 s6, s7
	s_cselect_b32 s6, s20, s6
	s_sub_i32 s20, s6, s7
	s_cmp_ge_u32 s6, s7
	s_cselect_b32 s6, s20, s6
	s_xor_b32 s6, s6, s13
	s_sub_i32 s6, s6, s13
	s_add_i32 s6, s6, s12
	v_lshl_add_u32 v2, s6, 8, v1
	v_lshlrev_b32_e32 v21, 6, v2
	global_load_dwordx4 v[48:51], v21, s[92:93]
	global_load_dwordx4 v[52:55], v21, s[92:93] offset:16
	global_load_dwordx4 v[56:59], v21, s[92:93] offset:32
	global_load_dwordx4 v[60:63], v21, s[92:93] offset:48
	v_add_u32_e32 v22, 0x1000, v21
	global_load_dwordx4 v[64:67], v22, s[92:93]
	global_load_dwordx4 v[68:71], v22, s[92:93] offset:16
	global_load_dwordx4 v[72:75], v22, s[92:93] offset:32
	global_load_dwordx4 v[76:79], v22, s[92:93] offset:48
	v_add_u32_e32 v23, 0x2000, v21
	global_load_dwordx4 v[80:83], v23, s[92:93]
	global_load_dwordx4 v[84:87], v23, s[92:93] offset:16
	global_load_dwordx4 v[88:91], v23, s[92:93] offset:32
	global_load_dwordx4 v[92:95], v23, s[92:93] offset:48
	v_add_u32_e32 v24, 0x3000, v21
	global_load_dwordx4 v[96:99], v24, s[92:93]
	global_load_dwordx4 v[100:103], v24, s[92:93] offset:16
	global_load_dwordx4 v[104:107], v24, s[92:93] offset:32
	global_load_dwordx4 v[108:111], v24, s[92:93] offset:48
	s_add_u32 s22, s22, s34
	s_addc_u32 s23, s23, s35
	s_waitcnt vmcnt(12)
	v_add_f32_e32 v48, v48, v49
	v_add_f32_e32 v50, v50, v51
	v_add_f32_e32 v48, v48, v50
	v_add_f32_e32 v52, v52, v53
	v_add_f32_e32 v54, v54, v55
	v_add_f32_e32 v52, v52, v54
	v_add_f32_e32 v56, v56, v57
	v_add_f32_e32 v58, v58, v59
	v_add_f32_e32 v56, v56, v58
	v_add_f32_e32 v60, v60, v61
	v_add_f32_e32 v62, v62, v63
	v_add_f32_e32 v60, v60, v62
	v_add_f32_e32 v48, v48, v52
	v_add_f32_e32 v48, v48, v56
	v_add_f32_e32 v48, v48, v60
	v_fmamk_f32 v48, v48, 0x3a800000, v217
	v_cmp_gt_f32_e32 vcc, 0x800000, v48
	v_mul_f32_e32 v49, 0x4b800000, v48
	s_nop 0
	v_cndmask_b32_e32 v48, v48, v49, vcc
	v_rsq_f32_e32 v48, v48
	s_nop 0
	v_mul_f32_e32 v49, 0x45800000, v48
	v_cndmask_b32_e32 v48, v48, v49, vcc
	ds_write_b32 v20, v48
	s_waitcnt vmcnt(8)
	v_add_f32_e32 v64, v64, v65
	v_add_f32_e32 v66, v66, v67
	v_add_f32_e32 v64, v64, v66
	v_add_f32_e32 v68, v68, v69
	v_add_f32_e32 v70, v70, v71
	v_add_f32_e32 v68, v68, v70
	v_add_f32_e32 v72, v72, v73
	v_add_f32_e32 v74, v74, v75
	v_add_f32_e32 v72, v72, v74
	v_add_f32_e32 v76, v76, v77
	v_add_f32_e32 v78, v78, v79
	v_add_f32_e32 v76, v76, v78
	v_add_f32_e32 v64, v64, v68
	v_add_f32_e32 v64, v64, v72
	v_add_f32_e32 v64, v64, v76
	v_fmamk_f32 v64, v64, 0x3a800000, v217
	v_cmp_gt_f32_e32 vcc, 0x800000, v64
	v_mul_f32_e32 v65, 0x4b800000, v64
	s_nop 0
	v_cndmask_b32_e32 v64, v64, v65, vcc
	v_rsq_f32_e32 v64, v64
	s_nop 0
	v_mul_f32_e32 v65, 0x45800000, v64
	v_cndmask_b32_e32 v64, v64, v65, vcc
	ds_write_b32 v20, v64 offset:256
	s_waitcnt vmcnt(4)
	v_add_f32_e32 v80, v80, v81
	v_add_f32_e32 v82, v82, v83
	v_add_f32_e32 v80, v80, v82
	v_add_f32_e32 v84, v84, v85
	v_add_f32_e32 v86, v86, v87
	v_add_f32_e32 v84, v84, v86
	v_add_f32_e32 v88, v88, v89
	v_add_f32_e32 v90, v90, v91
	v_add_f32_e32 v88, v88, v90
	v_add_f32_e32 v92, v92, v93
	v_add_f32_e32 v94, v94, v95
	v_add_f32_e32 v92, v92, v94
	v_add_f32_e32 v80, v80, v84
	v_add_f32_e32 v80, v80, v88
	v_add_f32_e32 v80, v80, v92
	v_fmamk_f32 v80, v80, 0x3a800000, v217
	v_cmp_gt_f32_e32 vcc, 0x800000, v80
	v_mul_f32_e32 v81, 0x4b800000, v80
	s_nop 0
	v_cndmask_b32_e32 v80, v80, v81, vcc
	v_rsq_f32_e32 v80, v80
	s_nop 0
	v_mul_f32_e32 v81, 0x45800000, v80
	v_cndmask_b32_e32 v80, v80, v81, vcc
	ds_write_b32 v20, v80 offset:512
	s_waitcnt vmcnt(0)
	v_add_f32_e32 v96, v96, v97
	v_add_f32_e32 v98, v98, v99
	v_add_f32_e32 v96, v96, v98
	v_add_f32_e32 v100, v100, v101
	v_add_f32_e32 v102, v102, v103
	v_add_f32_e32 v100, v100, v102
	v_add_f32_e32 v104, v104, v105
	v_add_f32_e32 v106, v106, v107
	v_add_f32_e32 v104, v104, v106
	v_add_f32_e32 v108, v108, v109
	v_add_f32_e32 v110, v110, v111
	v_add_f32_e32 v108, v108, v110
	v_add_f32_e32 v96, v96, v100
	v_add_f32_e32 v96, v96, v104
	v_add_f32_e32 v96, v96, v108
	v_fmamk_f32 v96, v96, 0x3a800000, v217
	v_cmp_gt_f32_e32 vcc, 0x800000, v96
	v_mul_f32_e32 v97, 0x4b800000, v96
	s_nop 0
	v_cndmask_b32_e32 v96, v96, v97, vcc
	v_rsq_f32_e32 v96, v96
	s_nop 0
	v_mul_f32_e32 v97, 0x45800000, v96
	v_cndmask_b32_e32 v96, v96, v97, vcc
	ds_write_b32 v20, v96 offset:768
	v_add_u32_e32 v20, 0x2000, v20
	s_branch .Lrsl4_loop
; #define PG8_STAGE(bufoff, gbase, voff) do { _Pragma("unroll") for (int _i = 0; _i < 2; ++_i) \
;     __builtin_amdgcn_global_load_lds((const unsigned*)((const char*)(gbase) + (voff)[_i]), (LAS unsigned*)(lds + (bufoff) + ldsw + _i * 8192), 16, 0, 0); } while (0)
; #define PG8_BAR __builtin_amdgcn_s_barrier()
; template <class Epi, class Sched>
; __device__ __forceinline__ void gemm_phase(LAS unsigned char* lds, const Gemm g, const Sched& S, const Epi& E) {
;     ...
;   for (int i = 0; i < 2; ++i) { int R, C; stage_rc(tid * 16 + i * 8192, R, C); const int Rb = Epi::PERM ? ((R & ~31) + perm32(R & 31)) : R;
;     voffA[i] = (unsigned)(R * K + C) * 2u; voffB[i] = (unsigned)(Rb * K + C) * 2u; }
;   const size_t kstep = (size_t)(BK * 2);
;   const size_t hstep = (size_t)HALF * K * 2;
;   const size_t tstep = 2 * hstep;
;   const unsigned ldsw = (unsigned)wid * 1024u;
;   const int aoff = lds_byte(wr * 64 + fr, fq * 8), boff = lds_byte(wc * 32 + fr, fq * 8);
;     ...
;   Unit cur, nxt; int ui = 0;
;   if (!S.next(0, cur)) return;
;   f32x4 acc[2][2][4][2];
; #pragma unroll
;   for (int a = 0; a < 2; ++a)
; #pragma unroll
;     for (int b = 0; b < 2; ++b)
; #pragma unroll
;       for (int m = 0; m < 4; ++m)
; #pragma unroll
;         for (int n = 0; n < 2; ++n) acc[a][b][m][n] = (f32x4){0.f, 0.f, 0.f, 0.f};
;   bf16x8 At[4][2], B0[2][2], B1[2][2];
;   const char* cA = (const char*)g.A + (size_t)cur.pm * tstep; const char* cB = (const char*)g.Bt + (size_t)cur.pn * tstep;
;   S.a_ready(cur);
;   PG8_STAGE(PG8_SB(0, 0), cB, voffB); PG8_STAGE(PG8_SA(0, 0), cA, voffA); PG8_STAGE(PG8_SB(0, 1), cB + hstep, voffB); PG8_STAGE(PG8_SA(0, 1), cA + hstep, voffA);
;   if (wr == 1) PG8_BAR;
; template <class Epi> __device__ __forceinline__ void run_gemm(LAS unsigned char* lds, const bf16_t* A, const bf16_t* Bt, int M, int N, int K, const Epi& E, const float* RSS = nullptr) {
;     ...
;     for (int i = 0; S.next(i, u); ++i) if (tid < 256) rsl[i * 256 + tid] = row_rstd(RSS, u.pm * 256 + tid);
;     __syncthreads();
.Lrsl4_done:
.LBB0_1135:
	v_readlane_b32 s12, v251, 59
	v_mov_b32_e32 v2, v214
	v_readlane_b32 s13, v251, 60
	s_waitcnt lgkmcnt(0)
	s_barrier
	s_and_b64 vcc, exec, s[12:13]
	v_readfirstlane_b32 s6, v2
	s_cbranch_vccz .LBB0_1147
	v_lshlrev_b32_e32 v4, 4, v2
	v_add_u32_e32 v1, 0x2000, v4
	v_ashrrev_i32_e32 v0, 31, v1
	v_lshrrev_b32_e32 v0, 22, v0
	v_add_u32_e32 v0, v1, v0
	v_ashrrev_i32_e32 v0, 10, v0
	v_mul_i32_i24_e32 v3, 0x400, v0
	v_sub_u32_e32 v1, v1, v3
	v_lshrrev_b32_e32 v3, 4, v1
	v_bitop3_b32 v3, v3, v1, 32 bitop3:0x6c
	v_ashrrev_i32_e32 v1, 31, v3
	v_lshrrev_b32_e32 v1, 26, v1
	v_add_u32_e32 v5, v3, v1
	v_lshlrev_b32_e32 v6, 3, v0
	v_ashrrev_i32_e32 v1, 6, v5
	v_and_b32_e32 v6, -16, v6
	v_add_u32_e32 v6, v1, v6
	v_and_b32_e32 v7, 3, v1
	s_mov_b32 s12, 0x1fffe0
	v_lshrrev_b32_e32 v8, 2, v6
	v_lshlrev_b32_e32 v9, 1, v6
	v_and_b32_e32 v5, 0xc0, v5
	v_and_or_b32 v7, v6, s12, v7
	v_and_b32_e32 v8, 4, v8
	v_and_b32_e32 v9, 24, v9
	v_sub_u32_e32 v3, v3, v5
	v_or3_b32 v7, v7, v8, v9
	v_lshlrev_b32_e32 v8, 5, v0
	v_ashrrev_i16_sdwa v3, v246, sext(v3) dst_sel:DWORD dst_unused:UNUSED_PAD src0_sel:DWORD src1_sel:BYTE_0
	v_and_b32_e32 v8, 32, v8
	v_bfe_i32 v3, v3, 0, 16
	v_add_lshl_u32 v5, v8, v3, 1
	v_lshl_add_u32 v128, v7, 11, v5
	v_lshl_add_u32 v130, v6, 11, v5
	v_bfe_i32 v5, v2, 27, 1
	v_lshrrev_b32_e32 v5, 22, v5
	v_add_u32_e32 v5, v4, v5
	v_and_b32_e32 v5, 0xfffffc00, v5
	v_sub_u32_e32 v4, v4, v5
	v_lshrrev_b32_e32 v5, 4, v4
	v_bitop3_b32 v6, v5, v4, 32 bitop3:0x6c
	v_ashrrev_i32_e32 v5, 31, v2
	v_lshrrev_b32_e32 v5, 26, v5
	v_ashrrev_i32_e32 v4, 31, v4
	v_add_u32_e32 v5, v2, v5
	v_lshrrev_b32_e32 v4, 26, v4
	v_ashrrev_i32_e32 v5, 6, v5
	v_add_u32_e32 v4, v6, v4
	v_lshlrev_b32_e32 v7, 3, v5
	v_ashrrev_i32_e32 v4, 6, v4
	v_and_b32_e32 v7, -16, v7
	v_add_u32_e32 v7, v4, v7
	v_and_b32_e32 v8, 3, v4
	v_lshrrev_b32_e32 v9, 2, v7
	v_lshlrev_b32_e32 v10, 1, v7
	v_and_or_b32 v8, v7, s12, v8
	v_and_b32_e32 v9, 4, v9
	v_and_b32_e32 v10, 24, v10
	v_or3_b32 v8, v8, v9, v10
	v_mul_i32_i24_e32 v10, 64, v4
	v_sub_u32_e32 v6, v6, v10
	s_ashr_i32 s20, s6, 6
	v_lshlrev_b32_e32 v9, 5, v5
	v_ashrrev_i16_sdwa v6, v246, sext(v6) dst_sel:DWORD dst_unused:UNUSED_PAD src0_sel:DWORD src1_sel:BYTE_0
	s_lshl_b32 s7, s20, 10
	v_and_b32_e32 v9, 32, v9
	v_bfe_i32 v6, v6, 0, 16
	v_add_lshl_u32 v9, v9, v6, 1
	s_add_i32 s12, s7, 0
	v_readlane_b32 s22, v252, 61
	v_lshl_add_u32 v132, v8, 11, v9
	s_add_i32 m0, s12, 0x10000
	v_readlane_b32 s23, v252, 62
	v_lshl_add_u32 v134, v7, 11, v9
	s_add_i32 s13, s12, 0x2000
	s_add_i32 s51, s12, 0x4000
	s_add_i32 s62, s12, 0x6000
	v_mov_b32_e32 v225, 1
	global_load_lds_dwordx4 v132, s[22:23]
	s_add_i32 m0, s12, 0x12000
	s_nop 0
	global_load_lds_dwordx4 v128, s[22:23]
	v_readlane_b32 s22, v252, 4
	s_mov_b32 m0, s12
	v_readlane_b32 s23, v252, 5
	s_nop 4
	global_load_lds_dwordx4 v134, s[22:23]
	s_mov_b32 m0, s13
	s_nop 0
	global_load_lds_dwordx4 v130, s[22:23]
	v_readlane_b32 s22, v252, 59
	s_add_i32 m0, s12, 0x14000
	v_readlane_b32 s23, v252, 60
	s_nop 4
	global_load_lds_dwordx4 v132, s[22:23]
	s_add_i32 m0, s12, 0x16000
	s_nop 0
	global_load_lds_dwordx4 v128, s[22:23]
	v_readlane_b32 s22, v252, 6
	s_mov_b32 m0, s51
	v_readlane_b32 s23, v252, 7
	s_nop 4
	global_load_lds_dwordx4 v134, s[22:23]
	s_mov_b32 m0, s62
	s_nop 0
	global_load_lds_dwordx4 v130, s[22:23]
	s_ashr_i32 s22, s6, 8
	s_cmp_lg_u32 s22, 1
	s_cbranch_scc1 .LBB0_1138
	s_barrier
